# v015 + attention work-item index remap: head taken from blockIdx&7 and segment/residue from (blockIdx>>3)&7, so consecutive workgroups read adjacent heads of the same token rows
# baseline (speedup 1.0000x reference)
; __device__ __forceinline__ void phase(LAS unsigned char* lds, const bf16* QKV, bf16* Og, float* L2, int tid) {
;     for (int it = blockIdx.x; it < 768; it += gridDim.x) {
;         const int g = it >> 8, idx = it & 255;
;         int bl, h, r, dil, n0, cnt, nseg = 1;
;         if (g == 0) { const int strip = idx >> 3; bl = strip >> 3; h = strip & 7; r = 0; dil = 1; n0 = 4 * (idx & 7); cnt = 4; }
;         else if (g == 1) { const int strip = idx >> 1; bl = strip >> 5; h = (strip >> 2) & 7; r = strip & 3; dil = 4; n0 = 4 * (idx & 1); cnt = 4; }
;         else { bl = idx >> 6; h = (idx >> 3) & 7; r = 2 * (idx & 7); dil = 16; n0 = 0; cnt = 2; nseg = 2; }
.LBB0_280:
	s_mov_b32 s99, s25
	s_bfe_u32 s98, s25, 0x30003
	s_andn2_b32 s25, s25, 63
	s_or_b32 s25, s25, s98
	s_and_b32 s98, s99, 7
	s_lshl_b32 s98, s98, 3
	s_or_b32 s25, s25, s98
	s_ashr_i32 s0, s25, 8
	s_cmpk_gt_u32 s25, 0xff
	s_mov_b64 s[20:21], -1
	s_cbranch_scc0 .LBB0_287
	s_cmp_lg_u32 s0, 1
	s_cbranch_scc0 .LBB0_283
	s_lshl_b32 s1, s25, 1
	s_and_b32 s22, s1, 14
	s_mov_b64 s[20:21], 0

; __device__ __forceinline__ unsigned swz(unsigned row) { return ((row & 3u) << 2) | ((row >> 2) & 3u); }
; __device__ __forceinline__ void segment(LAS unsigned char* lds, const bf16* __restrict__ QKV, bf16* __restrict__ Og, float* __restrict__ L2, int bl, int g, int h, int r, int dil, int n0, int cnt, int tid) {
;     const int lane = tid & 63, w = __builtin_amdgcn_readfirstlane(tid >> 6), lq = lane & 15, gq = lane >> 4;
;     const size_t rowbase = (size_t)bl * SEQ + r;
;     const bf16* qcol = QKV + (size_t)g * 3072 + h * 128;
;     const int srow = tid >> 4, sch = tid & 15;
;     const unsigned sdst = 256u * srow + 16u * ((unsigned)sch ^ swz(srow));
;     const unsigned sdstv = VBASE + 256u * srow + 16u * ((unsigned)sch ^ (2u * (srow & 7)));
;     unsigned koff[4], voff[8];
; #pragma unroll
;     for (int s = 0; s < 4; ++s) koff[s] = 256u * lq + 16u * ((unsigned)(4 * s + gq) ^ swz(lq));
;     { const unsigned q4 = lq >> 2, p4 = lq & 3, rowv = 4 * gq + q4;
; #pragma unroll
;       for (int c = 0; c < 8; ++c) voff[c] = 256u * rowv + 16u * ((unsigned)(2 * c + (p4 & 1)) ^ (2u * (rowv & 7))) + 8u * (p4 >> 1); }
;     const float cb = exp2f(-8.0f * (float)(g * 8 + h + 1) / 24.0f) * (float)dil * 1.4426950408889634f;
;     const float basel = -cb * (float)(128 + lq - 4 * gq);
;     v4u kv[8]; bf16x8 qn[4], qf[4];
;     ...
;             for (int i = 0; i < 4; ++i) { float v = sc[kt][i] + (basel + cb * (float)(16 * kt + i)); bool valid = true;
.LBB0_289:
	s_lshl_b32 s1, s1, 6
	s_and_b32 s29, s1, 0x3000
	v_writelane_b32 v238, s99, 2
	s_bfe_u32 s25, s25, 0x30003
	s_or_b32 s1, s29, s22
	s_lshl_b32 s28, s25, 2
	s_lshl_b32 s56, s25, 8
	v_writelane_b32 v238, s1, 3
	s_ashr_i32 s1, s0, 31
	s_mul_i32 s31, s0, 0x1800
	v_readlane_b32 s20, v239, 49
	s_mul_hi_i32 s30, s0, 0x1800
	v_readlane_b32 s21, v239, 50
	s_add_u32 s20, s20, s31
	s_addc_u32 s21, s21, s30
	s_add_u32 s20, s20, s56
	s_addc_u32 s21, s21, 0
	s_lshl_b32 s26, s0, 3
	s_or_b32 s25, s25, s26
	s_add_i32 s25, s25, 1
	v_cvt_f32_i32_e32 v0, s25
	s_mov_b32 s25, 0x41c00000
	v_lshl_add_u64 v[88:89], s[20:21], 0, v[74:75]
	v_lshl_add_u64 v[90:91], s[20:21], 0, v[76:77]
	v_mul_f32_e32 v0, 0xc1000000, v0
	v_div_scale_f32 v1, s[26:27], s25, s25, v0
	v_rcp_f32_e32 v2, v1
	s_mul_i32 s20, s54, 0x90000
	s_mov_b32 s21, s41
	s_mov_b32 s55, s41
	v_fma_f32 v4, -v1, v2, 1.0
	v_fmac_f32_e32 v2, v4, v2
	v_div_scale_f32 v4, vcc, v0, s25, v0
	v_mul_f32_e32 v5, v4, v2
	v_fma_f32 v6, -v1, v5, v4
	v_fmac_f32_e32 v5, v6, v2
	v_fma_f32 v1, -v1, v5, v4
	v_div_fmas_f32 v1, v1, v2, v5
	v_div_fixup_f32 v0, v1, s25, v0
	s_mov_b32 s25, 0xc2fc0000
	v_cmp_gt_f32_e32 vcc, s25, v0
	s_and_b64 s[26:27], vcc, exec
	s_cselect_b32 s25, 0xffffffc0, 0
	v_cndmask_b32_e32 v1, 0, v141, vcc
	v_add_f32_e32 v0, v0, v1
	v_exp_f32_e32 v0, v0
	v_cvt_f32_u32_e32 v1, s54
	s_cmp_lg_u32 s23, 0
	s_cselect_b64 s[26:27], -1, 0
	v_ldexp_f32 v0, v0, s25
	v_mul_f32_e32 v0, v0, v1
	v_mul_f32_e32 v0, 0x3fb8aa3b, v0
	s_add_i32 s33, s24, s23
	v_mul_f32_e32 v1, v0, v137
	s_mov_b32 s24, 0x40400000
	v_fma_f32 v146, v0, s24, -v1
	s_mov_b32 s24, 0x41800000
	v_fma_f32 v147, v0, s24, -v1
	s_mov_b32 s24, 0x41880000
	v_fma_f32 v148, v0, s24, -v1
	s_mov_b32 s24, 0x41900000
	v_fma_f32 v149, v0, s24, -v1
	s_mov_b32 s24, 0x41980000
	v_fma_f32 v150, v0, s24, -v1
	s_mov_b32 s24, 0x42000000
	v_fma_f32 v151, v0, s24, -v1
	s_mov_b32 s24, 0x42040000
	v_fma_f32 v152, v0, s24, -v1
	s_mov_b32 s24, 0x42080000
	v_fma_f32 v155, v0, s24, -v1
	s_mov_b32 s24, 0x420c0000
	v_fma_f32 v156, v0, s24, -v1
	s_mov_b32 s24, 0x42400000
	v_fma_f32 v157, v0, s24, -v1
	s_mov_b32 s24, 0x42440000
	v_fma_f32 v158, v0, s24, -v1
	s_mov_b32 s24, 0x42480000
	v_fma_f32 v159, v0, s24, -v1
	s_mov_b32 s24, 0x424c0000
	v_fma_f32 v160, v0, s24, -v1
	s_mov_b32 s24, 0x42800000
	v_fma_f32 v161, v0, s24, -v1
	s_mov_b32 s24, 0x42820000
	v_fma_f32 v162, v0, s24, -v1
	s_mov_b32 s24, 0x42840000
	v_fma_f32 v163, v0, s24, -v1
	s_mov_b32 s24, 0x42860000
	v_fma_f32 v164, v0, s24, -v1
	s_mov_b32 s24, 0x42a00000
	v_fma_f32 v165, v0, s24, -v1
	s_mov_b32 s24, 0x42a20000
	v_fma_f32 v166, v0, s24, -v1
	s_mov_b32 s24, 0x42a40000
	v_fma_f32 v167, v0, s24, -v1
	s_mov_b32 s24, 0x42a60000
	v_fma_f32 v168, v0, s24, -v1
	s_mov_b32 s24, 0x42c00000
	v_fma_f32 v169, v0, s24, -v1
	s_mov_b32 s24, 0x42c20000
	v_fma_f32 v170, v0, s24, -v1
	s_mov_b32 s24, 0x42c40000
	v_fma_f32 v171, v0, s24, -v1
	s_mov_b32 s24, 0x42c60000
	v_fma_f32 v172, v0, s24, -v1
	s_mov_b32 s24, 0x42e00000
	v_fma_f32 v173, v0, s24, -v1
	s_mov_b32 s24, 0x42e20000
	v_fma_f32 v174, v0, s24, -v1
	s_mov_b32 s24, 0x42e40000
	v_fma_f32 v175, v0, s24, -v1
	s_mov_b32 s24, 0x42e60000
	v_fma_f32 v176, v0, s24, -v1
	s_mov_b32 s24, 0x43000000
	v_fma_f32 v177, v0, s24, -v1
	s_mov_b32 s24, 0x43010000
	v_writelane_b32 v238, s26, 4
	v_fma_f32 v178, v0, s24, -v1
	s_mov_b32 s24, 0x43020000
	v_writelane_b32 v238, s27, 5
	v_fma_f32 v179, v0, s24, -v1
	s_mov_b32 s24, 0x43030000
	s_lshl_b32 s26, s23, 7
	v_fma_f32 v143, v0, 0, -v1
	v_fma_f32 v144, -v0, v137, v0
	v_fma_f32 v145, v0, 2.0, -v1
	v_fma_f32 v180, v0, s24, -v1
	v_add_u32_e32 v0, s26, v138
	v_mad_u64_u32 v[86:87], s[24:25], v0, s54, 0
	s_mul_i32 s24, s54, 0x48000
	s_mov_b32 s25, s41
	v_writelane_b32 v238, s24, 6
	s_lshl_b64 s[0:1], s[0:1], 14
	v_or_b32_e32 v2, s26, v122
	v_writelane_b32 v238, s25, 7
	v_writelane_b32 v238, s26, 8
	v_writelane_b32 v238, s20, 9
	s_mov_b32 s57, s41
	s_mov_b32 s47, 0
	v_writelane_b32 v238, s21, 10
	v_readlane_b32 s20, v239, 51
	v_readlane_b32 s21, v239, 52
	s_add_u32 s20, s20, s28
	s_addc_u32 s21, s21, 0
	v_writelane_b32 v238, s20, 11
	v_mul_u32_u24_e32 v181, s54, v2
	v_or_b32_e32 v182, s26, v119
	v_writelane_b32 v238, s21, 12
	s_add_i32 s20, s22, s29
	s_add_u32 s0, s0, s20
	s_addc_u32 s1, s1, 0
	v_writelane_b32 v238, s0, 13
	s_lshl_b64 s[78:79], s[54:55], 12
	s_lshl_b64 s[80:81], s[54:55], 18
	v_writelane_b32 v238, s1, 14
	s_add_i32 s0, s23, 1
	s_mul_hi_u32 s1, s20, 0x4800
	s_mulk_i32 s20, 0x4800
	v_writelane_b32 v238, s0, 15
	s_add_u32 s0, s20, s31
	s_addc_u32 s1, s1, s30
	s_or_b32 s20, s0, s56
	s_mov_b32 s21, s1
	s_movk_i32 s22, 0x4800
	v_lshl_add_u64 v[92:93], v[70:71], 0, s[20:21]
	v_mad_u64_u32 v[0:1], s[20:21], v2, s22, v[78:79]
	v_mov_b64_e32 v[4:5], s[0:1]
	v_mad_u64_u32 v[6:7], s[0:1], v0, s54, v[4:5]
	v_mov_b32_e32 v0, v7
	v_mad_u64_u32 v[0:1], s[0:1], v1, s54, v[0:1]
	v_mov_b32_e32 v7, v0
	v_mad_u64_u32 v[0:1], s[0:1], v2, s22, v[80:81]
	v_lshl_add_u64 v[94:95], v[72:73], 0, v[6:7]
	v_mad_u64_u32 v[6:7], s[0:1], v0, s54, v[4:5]
	v_mov_b32_e32 v0, v7
	v_mad_u64_u32 v[0:1], s[0:1], v1, s54, v[0:1]
	v_mov_b32_e32 v7, v0
	v_mad_u64_u32 v[0:1], s[0:1], v2, s22, v[82:83]
	v_lshl_add_u64 v[96:97], v[72:73], 0, v[6:7]
	v_mad_u64_u32 v[6:7], s[0:1], v0, s54, v[4:5]
	v_mov_b32_e32 v0, v7
	v_mad_u64_u32 v[0:1], s[0:1], v1, s54, v[0:1]
	v_mov_b32_e32 v7, v0
	v_mad_u64_u32 v[0:1], s[0:1], v2, s22, v[84:85]
	v_mad_u64_u32 v[4:5], s[0:1], v0, s54, v[4:5]
	v_mov_b32_e32 v0, v5
	v_mad_u64_u32 v[0:1], s[0:1], v1, s54, v[0:1]
	v_mov_b32_e32 v5, v0
	v_mul_u32_u24_e32 v183, s54, v122
	s_mul_hi_u32 s83, s54, 0x240000
	s_mul_i32 s82, s54, 0x240000
	v_lshl_add_u64 v[98:99], v[72:73], 0, v[6:7]
	v_lshl_add_u64 v[100:101], v[72:73], 0, v[4:5]
	s_branch .LBB0_291

; __device__ __forceinline__ unsigned swz(unsigned row) { return ((row & 3u) << 2) | ((row >> 2) & 3u); }
; __device__ __forceinline__ void segment(LAS unsigned char* lds, const bf16* __restrict__ QKV, bf16* __restrict__ Og, float* __restrict__ L2, int bl, int g, int h, int r, int dil, int n0, int cnt, int tid) {
;     const int lane = tid & 63, w = __builtin_amdgcn_readfirstlane(tid >> 6), lq = lane & 15, gq = lane >> 4;
;     const size_t rowbase = (size_t)bl * SEQ + r;
;     const bf16* qcol = QKV + (size_t)g * 3072 + h * 128;
;     const int srow = tid >> 4, sch = tid & 15;
;     const unsigned sdst = 256u * srow + 16u * ((unsigned)sch ^ swz(srow));
;     const unsigned sdstv = VBASE + 256u * srow + 16u * ((unsigned)sch ^ (2u * (srow & 7)));
;     unsigned koff[4], voff[8];
; #pragma unroll
;     for (int s = 0; s < 4; ++s) koff[s] = 256u * lq + 16u * ((unsigned)(4 * s + gq) ^ swz(lq));
;     { const unsigned q4 = lq >> 2, p4 = lq & 3, rowv = 4 * gq + q4;
; #pragma unroll
;       for (int c = 0; c < 8; ++c) voff[c] = 256u * rowv + 16u * ((unsigned)(2 * c + (p4 & 1)) ^ (2u * (rowv & 7))) + 8u * (p4 >> 1); }
;     const float cb = exp2f(-8.0f * (float)(g * 8 + h + 1) / 24.0f) * (float)dil * 1.4426950408889634f;
;     const float basel = -cb * (float)(128 + lq - 4 * gq);
;     v4u kv[8]; bf16x8 qn[4], qf[4];
;     ...
;             for (int i = 0; i < 4; ++i) { float v = sc[kt][i] + (basel + cb * (float)(16 * kt + i)); bool valid = true;
.LBB0_443:
	s_lshl_b32 s1, s1, 6
	s_and_b32 s29, s1, 0x3000
	v_writelane_b32 v238, s99, 2
	s_bfe_u32 s25, s25, 0x30003
	s_or_b32 s1, s29, s22
	s_lshl_b32 s28, s25, 2
	s_lshl_b32 s56, s25, 8
	v_writelane_b32 v238, s1, 3
	s_ashr_i32 s1, s0, 31
	s_mul_i32 s31, s0, 0x1800
	v_readlane_b32 s20, v239, 49
	s_mul_hi_i32 s30, s0, 0x1800
	v_readlane_b32 s21, v239, 50
	s_add_u32 s20, s20, s31
	s_addc_u32 s21, s21, s30
	s_add_u32 s20, s20, s56
	s_addc_u32 s21, s21, 0
	s_lshl_b32 s26, s0, 3
	s_or_b32 s25, s25, s26
	s_add_i32 s25, s25, 1
	v_cvt_f32_i32_e32 v0, s25
	s_mov_b32 s25, 0x41c00000
	v_lshl_add_u64 v[88:89], s[20:21], 0, v[74:75]
	v_lshl_add_u64 v[90:91], s[20:21], 0, v[76:77]
	v_mul_f32_e32 v0, 0xc1000000, v0
	v_div_scale_f32 v1, s[26:27], s25, s25, v0
	v_rcp_f32_e32 v2, v1
	s_mul_i32 s20, s54, 0x90000
	s_mov_b32 s21, s41
	s_mov_b32 s55, s41
	v_fma_f32 v4, -v1, v2, 1.0
	v_fmac_f32_e32 v2, v4, v2
	v_div_scale_f32 v4, vcc, v0, s25, v0
	v_mul_f32_e32 v5, v4, v2
	v_fma_f32 v6, -v1, v5, v4
	v_fmac_f32_e32 v5, v6, v2
	v_fma_f32 v1, -v1, v5, v4
	v_div_fmas_f32 v1, v1, v2, v5
	v_div_fixup_f32 v0, v1, s25, v0
	s_mov_b32 s25, 0xc2fc0000
	v_cmp_gt_f32_e32 vcc, s25, v0
	s_and_b64 s[26:27], vcc, exec
	s_cselect_b32 s25, 0xffffffc0, 0
	v_cndmask_b32_e32 v1, 0, v141, vcc
	v_add_f32_e32 v0, v0, v1
	v_exp_f32_e32 v0, v0
	v_cvt_f32_u32_e32 v1, s54
	s_cmp_lg_u32 s23, 0
	s_cselect_b64 s[26:27], -1, 0
	v_ldexp_f32 v0, v0, s25
	v_mul_f32_e32 v0, v0, v1
	v_mul_f32_e32 v0, 0x3fb8aa3b, v0
	s_add_i32 s33, s24, s23
	v_mul_f32_e32 v1, v0, v137
	s_mov_b32 s24, 0x40400000
	v_fma_f32 v146, v0, s24, -v1
	s_mov_b32 s24, 0x41800000
	v_fma_f32 v147, v0, s24, -v1
	s_mov_b32 s24, 0x41880000
	v_fma_f32 v148, v0, s24, -v1
	s_mov_b32 s24, 0x41900000
	v_fma_f32 v149, v0, s24, -v1
	s_mov_b32 s24, 0x41980000
	v_fma_f32 v150, v0, s24, -v1
	s_mov_b32 s24, 0x42000000
	v_fma_f32 v151, v0, s24, -v1
	s_mov_b32 s24, 0x42040000
	v_fma_f32 v152, v0, s24, -v1
	s_mov_b32 s24, 0x42080000
	v_fma_f32 v156, v0, s24, -v1
	s_mov_b32 s24, 0x420c0000
	v_fma_f32 v157, v0, s24, -v1
	s_mov_b32 s24, 0x42400000
	v_fma_f32 v158, v0, s24, -v1
	s_mov_b32 s24, 0x42440000
	v_fma_f32 v159, v0, s24, -v1
	s_mov_b32 s24, 0x42480000
	v_fma_f32 v160, v0, s24, -v1
	s_mov_b32 s24, 0x424c0000
	v_fma_f32 v161, v0, s24, -v1
	s_mov_b32 s24, 0x42800000
	v_fma_f32 v162, v0, s24, -v1
	s_mov_b32 s24, 0x42820000
	v_fma_f32 v163, v0, s24, -v1
	s_mov_b32 s24, 0x42840000
	v_fma_f32 v164, v0, s24, -v1
	s_mov_b32 s24, 0x42860000
	v_fma_f32 v165, v0, s24, -v1
	s_mov_b32 s24, 0x42a00000
	v_fma_f32 v166, v0, s24, -v1
	s_mov_b32 s24, 0x42a20000
	v_fma_f32 v167, v0, s24, -v1
	s_mov_b32 s24, 0x42a40000
	v_fma_f32 v168, v0, s24, -v1
	s_mov_b32 s24, 0x42a60000
	v_fma_f32 v169, v0, s24, -v1
	s_mov_b32 s24, 0x42c00000
	v_fma_f32 v170, v0, s24, -v1
	s_mov_b32 s24, 0x42c20000
	v_fma_f32 v171, v0, s24, -v1
	s_mov_b32 s24, 0x42c40000
	v_fma_f32 v172, v0, s24, -v1
	s_mov_b32 s24, 0x42c60000
	v_fma_f32 v173, v0, s24, -v1
	s_mov_b32 s24, 0x42e00000
	v_fma_f32 v174, v0, s24, -v1
	s_mov_b32 s24, 0x42e20000
	v_fma_f32 v175, v0, s24, -v1
	s_mov_b32 s24, 0x42e40000
	v_fma_f32 v176, v0, s24, -v1
	s_mov_b32 s24, 0x42e60000
	v_fma_f32 v177, v0, s24, -v1
	s_mov_b32 s24, 0x43000000
	v_fma_f32 v178, v0, s24, -v1
	s_mov_b32 s24, 0x43010000
	v_writelane_b32 v238, s26, 4
	v_fma_f32 v179, v0, s24, -v1
	s_mov_b32 s24, 0x43020000
	v_writelane_b32 v238, s27, 5
	v_fma_f32 v180, v0, s24, -v1
	s_mov_b32 s24, 0x43030000
	s_lshl_b32 s26, s23, 7
	v_fma_f32 v143, v0, 0, -v1
	v_fma_f32 v144, -v0, v137, v0
	v_fma_f32 v145, v0, 2.0, -v1
	v_fma_f32 v181, v0, s24, -v1
	v_add_u32_e32 v0, s26, v138
	v_mad_u64_u32 v[86:87], s[24:25], v0, s54, 0
	s_mul_i32 s24, s54, 0x48000
	s_mov_b32 s25, s41
	v_writelane_b32 v238, s24, 6
	s_lshl_b64 s[0:1], s[0:1], 14
	v_or_b32_e32 v2, s26, v122
	v_writelane_b32 v238, s25, 7
	v_writelane_b32 v238, s26, 8
	v_writelane_b32 v238, s20, 9
	s_mov_b32 s57, s41
	s_mov_b32 s47, 0
	v_writelane_b32 v238, s21, 10
	v_readlane_b32 s20, v239, 51
	v_readlane_b32 s21, v239, 52
	s_add_u32 s20, s20, s28
	s_addc_u32 s21, s21, 0
	v_writelane_b32 v238, s20, 11
	v_mul_u32_u24_e32 v182, s54, v2
	v_or_b32_e32 v183, s26, v119
	v_writelane_b32 v238, s21, 12
	s_add_i32 s20, s22, s29
	s_add_u32 s0, s0, s20
	s_addc_u32 s1, s1, 0
	v_writelane_b32 v238, s0, 13
	s_lshl_b64 s[76:77], s[54:55], 12
	s_lshl_b64 s[78:79], s[54:55], 18
	v_writelane_b32 v238, s1, 14
	s_add_i32 s0, s23, 1
	s_mul_hi_u32 s1, s20, 0x4800
	s_mulk_i32 s20, 0x4800
	v_writelane_b32 v238, s0, 15
	s_add_u32 s0, s20, s31
	s_addc_u32 s1, s1, s30
	s_or_b32 s20, s0, s56
	s_mov_b32 s21, s1
	s_movk_i32 s22, 0x4800
	v_lshl_add_u64 v[92:93], v[70:71], 0, s[20:21]
	v_mad_u64_u32 v[0:1], s[20:21], v2, s22, v[78:79]
	v_mov_b64_e32 v[4:5], s[0:1]
	v_mad_u64_u32 v[6:7], s[0:1], v0, s54, v[4:5]
	v_mov_b32_e32 v0, v7
	v_mad_u64_u32 v[0:1], s[0:1], v1, s54, v[0:1]
	v_mov_b32_e32 v7, v0
	v_mad_u64_u32 v[0:1], s[0:1], v2, s22, v[80:81]
	v_lshl_add_u64 v[94:95], v[72:73], 0, v[6:7]
	v_mad_u64_u32 v[6:7], s[0:1], v0, s54, v[4:5]
	v_mov_b32_e32 v0, v7
	v_mad_u64_u32 v[0:1], s[0:1], v1, s54, v[0:1]
	v_mov_b32_e32 v7, v0
	v_mad_u64_u32 v[0:1], s[0:1], v2, s22, v[82:83]
	v_lshl_add_u64 v[96:97], v[72:73], 0, v[6:7]
	v_mad_u64_u32 v[6:7], s[0:1], v0, s54, v[4:5]
	v_mov_b32_e32 v0, v7
	v_mad_u64_u32 v[0:1], s[0:1], v1, s54, v[0:1]
	v_mov_b32_e32 v7, v0
	v_mad_u64_u32 v[0:1], s[0:1], v2, s22, v[84:85]
	v_mad_u64_u32 v[4:5], s[0:1], v0, s54, v[4:5]
	v_mov_b32_e32 v0, v5
	v_mad_u64_u32 v[0:1], s[0:1], v1, s54, v[0:1]
	v_mov_b32_e32 v5, v0
	v_mul_u32_u24_e32 v184, s54, v122
	s_mul_hi_u32 s81, s54, 0x240000
	s_mul_i32 s80, s54, 0x240000
	v_lshl_add_u64 v[98:99], v[72:73], 0, v[6:7]
	v_lshl_add_u64 v[100:101], v[72:73], 0, v[4:5]
	s_branch .LBB0_445
